# strategy: static s_setprio 1 built for the other wave half (waves 0-3) over the attention prompt loop, to compare with the waves 4-7 build
# baseline (speedup 1.0000x reference)
; #define GRAB(dst) do { if (tid == 0) *nl = (int)__hip_atomic_fetch_add(qctr, 1u, __ATOMIC_RELAXED, __HIP_MEMORY_SCOPE_AGENT); __syncthreads(); dst = __builtin_amdgcn_readfirstlane(*nl); __syncthreads(); } while (0)
; __global__ void __launch_bounds__(512, 2) fox_fwd(Args args) {
;     ...
;             fox::Seam S; unsigned* qctr = (unsigned*)(ws + WS_QUEUE); const float* QN = (const float*)(ws + WS_QN); const float* KN = (const float*)(ws + WS_KN);
;             int* nl = (int*)((char*)lds + fox::LDS_BIAS - 32);
;             auto mkref = [&](int n) { const int bh = n & 31, qb = 31 - (n >> 5), b = bh >> 3, h = bh & 7;
;                 fox::BlockRef r; r.K = Kb + (size_t)bh * SEQ * HD; r.O = MIX + ((size_t)b * SEQ + (size_t)qb * 256) * DM + h * HD; r.C = Cp + (size_t)bh * SEQ; r.P0 = qb * 256;
;                 r.nrm = 1.02f * fox::SCALE * sqrtf(QN[bh * 32 + qb] * KN[bh]); return r; };
;     ...
;             int n; GRAB(n);
;             if (n < NB * NH * 32) {
;                 fox::BlockRef cur = mkref(n);
;                 fox::prime(cur, (char*)lds, S);
;                 for (;;) {
;                     int nn; GRAB(nn); const bool last = nn >= NB * NH * 32;
;                     const fox::BlockRef nxt = last ? cur : mkref(nn);
;                     fox::block(cur, nxt, (char*)lds, S);
.Lp5_prompt:
	v_readfirstlane_b32 s98, v182
	s_nop 3
	s_lshr_b32 s98, s98, 6
	s_cmp_lt_u32 s98, 4
	s_cbranch_scc0 .Lp5_prio_done
	s_setprio 1
